# expert gather loop pipelined: next pass's row indices prefetched, gate-value load issued with the row loads (3 dependent memory round trips per pass -> 1)
# baseline (speedup 1.0000x reference)
; #define LAS __attribute__((address_space(3)))
; DI void phase_gather(KArgs args, LAS unsigned char* L, const Ctx& c) {
;     const int lane = c.lane; const int* IDX = WSP(int, WS_IDX); const bf16_t* XB = WSP(bf16_t, WS_XB);
;     float* GATEV = WSP(float, WS_GATEV); int* SLOT = WSP(int, WS_SLOT); const float* AFF = WSP(float, WS_AFF);
;     for (int row0 = (c.bid * 8 + c.wave) * 4; row0 < NE * CAP; row0 += c.G * 8 * 4) {
;         const int e = row0 / CAP, s0 = row0 % CAP; int t[4]; u32x4 a[4], b[4];
; #pragma unroll
;         for (int k = 0; k < 4; ++k) t[k] = IDX[row0 + k];
; #pragma unroll
;         for (int k = 0; k < 4; ++k) { const u32x4* src = (const u32x4*)(XB + (size_t)t[k] * D) + 2 * lane; a[k] = src[0]; b[k] = src[1]; }
.LBB0_1445:
	s_andn2_b64 vcc, exec, s[0:1]
	s_cbranch_vccnz .LBB0_1503
	v_mov_b32_e32 v1, v0
	s_mov_b64 s[2:3], s[80:81]
	v_readfirstlane_b32 s0, v1
	s_mov_b32 s4, s78
	s_mov_b32 s1, s79
	s_ashr_i32 s0, s0, 4
	s_lshl_b32 s4, s4, 5
	s_and_b32 s0, s0, -4
	s_add_i32 s0, s4, s0
	s_cmp_gt_i32 s0, 0x27fff
	s_cbranch_scc1 .LBB0_1455
	s_load_dwordx2 s[6:7], s[2:3], 0xa8
	v_and_b32_e32 v32, 63, v1
	v_lshlrev_b32_e32 v2, 5, v32
	s_mov_b64 s[2:3], 0xd200000
	v_cmp_gt_u32_e32 vcc, 4, v32
	s_waitcnt lgkmcnt(0)
	s_add_u32 s16, s6, 0x17c00000
	v_lshl_add_u64 v[4:5], s[6:7], 0, v[2:3]
	s_addc_u32 s17, s7, 0
	v_lshl_add_u64 v[34:35], v[4:5], 0, s[2:3]
	s_add_u32 s2, s6, 0x17d00000
	s_addc_u32 s3, s7, 0
	s_add_u32 s8, s6, 0x17700000
	s_addc_u32 s9, s7, 0
	s_add_u32 s18, s6, 0x17200000
	s_addc_u32 s19, s7, 0
	s_add_u32 s20, s6, 0x18200000
	v_cmp_eq_u32_e64 s[4:5], 2, v32
	s_addc_u32 s21, s7, 0
	s_lshl_b32 s22, s1, 5
	s_ashr_i32 s1, s0, 31
	s_lshl_b64 s[6:7], s[0:1], 2
	s_add_u32 s6, s16, s6
	s_addc_u32 s7, s17, s7
	global_load_dwordx4 v[4:7], v3, s[6:7]
	s_waitcnt vmcnt(0)
; DI float bflo(unsigned u) { return __uint_as_float(u << 16); }
; DI float bfhi(unsigned u) { return __uint_as_float(u & 0xffff0000u); }
; DI void phase_gather(KArgs args, LAS unsigned char* L, const Ctx& c) {
;     ...
;     for (int row0 = (c.bid * 8 + c.wave) * 4; row0 < NE * CAP; row0 += c.G * 8 * 4) {
;         const int e = row0 / CAP, s0 = row0 % CAP; int t[4]; u32x4 a[4], b[4];
; #pragma unroll
;         for (int k = 0; k < 4; ++k) t[k] = IDX[row0 + k];
; #pragma unroll
;         for (int k = 0; k < 4; ++k) { const u32x4* src = (const u32x4*)(XB + (size_t)t[k] * D) + 2 * lane; a[k] = src[0]; b[k] = src[1]; }
;         u32x4* dst = (u32x4*)(BIGP(unsigned char, (e < 8 ? B_XY0 : B_XY1)) + ((size_t)(e & 7) * CAP + s0) * D);
; #pragma unroll
;         for (int k = 0; k < 4; ++k) { u32x4 w;
;             w.x = pk4_fp8(bflo(a[k].x), bfhi(a[k].x), bflo(a[k].y), bfhi(a[k].y)); w.y = pk4_fp8(bflo(a[k].z), bfhi(a[k].z), bflo(a[k].w), bfhi(a[k].w));
;             w.z = pk4_fp8(bflo(b[k].x), bfhi(b[k].x), bflo(b[k].y), bfhi(b[k].y)); w.w = pk4_fp8(bflo(b[k].z), bfhi(b[k].z), bflo(b[k].w), bfhi(b[k].w));
;             dst[k * 64 + lane] = w; }
;         if (lane < 4) { const int tt = (lane == 0) ? t[0] : (lane == 1) ? t[1] : (lane == 2) ? t[2] : t[3]; SLOT[(size_t)tt * 16 + e] = s0 + lane; GATEV[row0 + lane] = AFF[(size_t)e * T_ALL + tt]; } }
.LBB0_1451:
	s_mul_hi_i32 s1, s0, 0x66666667
	s_lshr_b32 s6, s1, 31
	s_ashr_i32 s1, s1, 12
	s_add_i32 s10, s1, s6
	s_add_i32 s24, s0, s22
	s_ashr_i32 s25, s24, 31
	s_lshl_b64 s[24:25], s[24:25], 2
	s_add_u32 s24, s16, s24
	s_addc_u32 s25, s17, s25
	global_load_dwordx4 v[48:51], v3, s[24:25]
	s_mul_i32 s14, s10, 0x50000
	s_mul_hi_i32 s15, s10, 0x50000
	s_add_u32 s14, s18, s14
	s_addc_u32 s15, s19, s15
	s_mul_i32 s1, s10, 0xffffd800
	s_add_i32 s6, s0, s1
	s_cmp_lt_i32 s0, 0x14000
	s_cselect_b32 s7, 0, 0xa000000
	s_add_u32 s11, s20, s7
	s_addc_u32 s12, s21, 0
	s_and_b32 s7, s10, 7
	s_mulk_i32 s7, 0x2800
	s_ashr_i32 s13, s6, 31
	s_add_u32 s6, s7, s6
	s_addc_u32 s7, 0, s13
	s_lshl_b64 s[6:7], s[6:7], 10
	s_add_u32 s6, s11, s6
	s_addc_u32 s7, s12, s7
	v_mov_b32_e32 v54, v7
	v_cmp_eq_u32_e64 s[12:13], 1, v32
	v_cndmask_b32_e64 v54, v54, v6, s[4:5]
	s_nop 0
	v_cndmask_b32_e64 v54, v54, v5, s[12:13]
	v_cmp_eq_u32_e64 s[12:13], 0, v32
	s_nop 1
	v_cndmask_b32_e64 v54, v54, v4, s[12:13]
	v_ashrrev_i32_e32 v55, 31, v54
	v_ashrrev_i32_e32 v37, 31, v4
	v_mov_b32_e32 v36, v4
	v_lshlrev_b64 v[10:11], 11, v[36:37]
	v_lshl_add_u64 v[10:11], v[34:35], 0, v[10:11]
	global_load_dwordx4 v[40:43], v[10:11], off offset:16
	global_load_dwordx4 v[44:47], v[10:11], off
	v_ashrrev_i32_e32 v39, 31, v5
	v_mov_b32_e32 v38, v5
	v_lshlrev_b64 v[8:9], 11, v[38:39]
	v_lshl_add_u64 v[8:9], v[34:35], 0, v[8:9]
	global_load_dwordx4 v[24:27], v[8:9], off offset:16
	global_load_dwordx4 v[28:31], v[8:9], off
	v_ashrrev_i32_e32 v9, 31, v6
	v_mov_b32_e32 v8, v6
	v_lshlrev_b64 v[8:9], 11, v[8:9]
	v_lshl_add_u64 v[8:9], v[34:35], 0, v[8:9]
	global_load_dwordx4 v[16:19], v[8:9], off offset:16
	global_load_dwordx4 v[20:23], v[8:9], off
	v_ashrrev_i32_e32 v11, 31, v7
	v_mov_b32_e32 v10, v7
	v_lshlrev_b64 v[10:11], 11, v[10:11]
	v_lshl_add_u64 v[12:13], v[34:35], 0, v[10:11]
	global_load_dwordx4 v[8:11], v[12:13], off offset:16
	s_nop 0
	global_load_dwordx4 v[12:15], v[12:13], off
	v_lshl_add_u64 v[56:57], v[54:55], 2, s[14:15]
	global_load_dword v52, v[56:57], off
	s_waitcnt vmcnt(7)
	v_lshlrev_b32_e32 v1, 16, v44
	v_and_b32_e32 v2, 0xffff0000, v44
	v_mov_b32_e32 v44, v3
	v_cvt_pk_fp8_f32 v44, v1, v2
	v_lshlrev_b32_e32 v33, 16, v45
	v_and_b32_e32 v36, 0xffff0000, v45
	v_lshlrev_b32_e32 v1, 16, v46
	v_and_b32_e32 v2, 0xffff0000, v46
	v_mov_b32_e32 v45, v3
	v_cvt_pk_fp8_f32 v45, v1, v2
	v_lshlrev_b32_e32 v1, 16, v40
	v_and_b32_e32 v2, 0xffff0000, v40
	v_mov_b32_e32 v46, v3
	v_cvt_pk_fp8_f32 v44, v33, v36 op_sel:[0,0,1]
	v_lshlrev_b32_e32 v33, 16, v47
	v_and_b32_e32 v36, 0xffff0000, v47
	v_cvt_pk_fp8_f32 v46, v1, v2
	v_lshlrev_b32_e32 v1, 16, v42
	v_and_b32_e32 v2, 0xffff0000, v42
	v_mov_b32_e32 v47, v3
	v_cvt_pk_fp8_f32 v47, v1, v2
	v_cvt_pk_fp8_f32 v45, v33, v36 op_sel:[0,0,1]
	v_lshlrev_b32_e32 v33, 16, v41
	v_and_b32_e32 v36, 0xffff0000, v41
	v_cvt_pk_fp8_f32 v46, v33, v36 op_sel:[0,0,1]
	v_lshlrev_b32_e32 v33, 16, v43
	v_and_b32_e32 v36, 0xffff0000, v43
	v_cvt_pk_fp8_f32 v47, v33, v36 op_sel:[0,0,1]
	s_waitcnt vmcnt(5)
	v_lshlrev_b32_e32 v2, 16, v28
	v_and_b32_e32 v33, 0xffff0000, v28
	v_mov_b32_e32 v28, v3
	v_cvt_pk_fp8_f32 v28, v2, v33
	v_lshlrev_b32_e32 v36, 16, v29
	v_and_b32_e32 v29, 0xffff0000, v29
	v_lshlrev_b32_e32 v2, 16, v30
	v_cvt_pk_fp8_f32 v28, v36, v29 op_sel:[0,0,1]
	v_and_b32_e32 v30, 0xffff0000, v30
	v_mov_b32_e32 v29, v3
	v_cvt_pk_fp8_f32 v29, v2, v30
	v_lshlrev_b32_e32 v2, 16, v24
	v_and_b32_e32 v24, 0xffff0000, v24
	v_mov_b32_e32 v30, v3
	v_cvt_pk_fp8_f32 v30, v2, v24
	v_lshlrev_b32_e32 v33, 16, v31
	v_and_b32_e32 v31, 0xffff0000, v31
	v_cvt_pk_fp8_f32 v29, v33, v31 op_sel:[0,0,1]
	v_lshlrev_b32_e32 v31, 16, v25
	v_and_b32_e32 v25, 0xffff0000, v25
	v_cvt_pk_fp8_f32 v30, v31, v25 op_sel:[0,0,1]
	v_lshlrev_b32_e32 v2, 16, v26
	v_and_b32_e32 v24, 0xffff0000, v26
	v_mov_b32_e32 v31, v3
	v_cvt_pk_fp8_f32 v31, v2, v24
	s_waitcnt vmcnt(3)
	v_lshlrev_b32_e32 v2, 16, v20
	v_and_b32_e32 v24, 0xffff0000, v20
	v_mov_b32_e32 v20, v3
	v_cvt_pk_fp8_f32 v20, v2, v24
	v_lshlrev_b32_e32 v25, 16, v27
	v_and_b32_e32 v26, 0xffff0000, v27
	v_cvt_pk_fp8_f32 v31, v25, v26 op_sel:[0,0,1]
	v_lshlrev_b32_e32 v25, 16, v21
	v_and_b32_e32 v21, 0xffff0000, v21
	v_cvt_pk_fp8_f32 v20, v25, v21 op_sel:[0,0,1]
	v_lshlrev_b32_e32 v2, 16, v22
	v_and_b32_e32 v22, 0xffff0000, v22
	v_mov_b32_e32 v21, v3
	v_cvt_pk_fp8_f32 v21, v2, v22
	v_lshlrev_b32_e32 v2, 16, v16
	v_and_b32_e32 v16, 0xffff0000, v16
	v_mov_b32_e32 v22, v3
	v_cvt_pk_fp8_f32 v22, v2, v16
	v_lshlrev_b32_e32 v24, 16, v23
	v_and_b32_e32 v23, 0xffff0000, v23
	v_cvt_pk_fp8_f32 v21, v24, v23 op_sel:[0,0,1]
	v_lshlrev_b32_e32 v23, 16, v17
	v_and_b32_e32 v17, 0xffff0000, v17
	v_cvt_pk_fp8_f32 v22, v23, v17 op_sel:[0,0,1]
	v_lshlrev_b32_e32 v2, 16, v18
	v_and_b32_e32 v16, 0xffff0000, v18
	v_mov_b32_e32 v23, v3
	v_cvt_pk_fp8_f32 v23, v2, v16
	s_waitcnt vmcnt(1)
	v_lshlrev_b32_e32 v2, 16, v12
	v_and_b32_e32 v16, 0xffff0000, v12
	v_mov_b32_e32 v12, v3
	v_cvt_pk_fp8_f32 v12, v2, v16
	v_lshlrev_b32_e32 v17, 16, v19
	v_and_b32_e32 v18, 0xffff0000, v19
	v_cvt_pk_fp8_f32 v23, v17, v18 op_sel:[0,0,1]
	v_lshlrev_b32_e32 v17, 16, v13
	v_and_b32_e32 v13, 0xffff0000, v13
	v_cvt_pk_fp8_f32 v12, v17, v13 op_sel:[0,0,1]
	v_lshlrev_b32_e32 v2, 16, v14
	v_and_b32_e32 v14, 0xffff0000, v14
	v_mov_b32_e32 v13, v3
	v_cvt_pk_fp8_f32 v13, v2, v14
	v_lshlrev_b32_e32 v2, 16, v8
	v_and_b32_e32 v8, 0xffff0000, v8
	v_mov_b32_e32 v14, v3
	v_cvt_pk_fp8_f32 v14, v2, v8
	v_lshlrev_b32_e32 v16, 16, v15
	v_and_b32_e32 v15, 0xffff0000, v15
	v_cvt_pk_fp8_f32 v13, v16, v15 op_sel:[0,0,1]
	v_lshlrev_b32_e32 v15, 16, v9
	v_and_b32_e32 v9, 0xffff0000, v9
	v_cvt_pk_fp8_f32 v14, v15, v9 op_sel:[0,0,1]
	v_lshlrev_b32_e32 v2, 16, v10
	v_and_b32_e32 v8, 0xffff0000, v10
	v_mov_b32_e32 v15, v3
	v_cvt_pk_fp8_f32 v15, v2, v8
	v_lshlrev_b32_e32 v9, 16, v11
	v_and_b32_e32 v10, 0xffff0000, v11
	v_lshlrev_b32_e32 v1, 4, v32
	v_cvt_pk_fp8_f32 v15, v9, v10 op_sel:[0,0,1]
	global_store_dwordx4 v1, v[44:47], s[6:7]
	global_store_dwordx4 v1, v[28:31], s[6:7] offset:1024
	global_store_dwordx4 v1, v[20:23], s[6:7] offset:2048
	global_store_dwordx4 v1, v[12:15], s[6:7] offset:3072
	s_and_saveexec_b64 s[12:13], vcc
	s_cbranch_execz .Lg_skip
	v_add_u32_e32 v56, s0, v32
	v_lshlrev_b64 v[58:59], 6, v[54:55]
	s_ashr_i32 s11, s10, 31
	v_lshl_add_u64 v[58:59], s[8:9], 0, v[58:59]
	v_lshl_add_u64 v[58:59], s[10:11], 2, v[58:59]
	v_add_u32_e32 v60, s1, v56
	global_store_dword v[58:59], v60, off
	v_ashrrev_i32_e32 v57, 31, v56
	v_lshl_add_u64 v[56:57], v[56:57], 2, s[2:3]
	s_waitcnt vmcnt(5)
	global_store_dword v[56:57], v52, off
.Lg_skip:
	s_or_b64 exec, exec, s[12:13]
	v_mov_b32_e32 v4, v48
	v_mov_b32_e32 v5, v49
	v_mov_b32_e32 v6, v50
	v_mov_b32_e32 v7, v51
	s_add_i32 s0, s0, s22
	s_cmp_lt_i32 s0, 0x28000
	s_cbranch_scc1 .LBB0_1451
